# grid barrier v2: acquire (buffer_inv) issued at arrival, overlapped with the arrival atomic; all WGs poll TOP
# speedup vs baseline: 1.0127x; 1.0079x over previous
.LBB0_367:
	s_cmp_gt_i32 s79, 2
	s_cselect_b64 s[4:5], -1, 0
	s_and_b64 s[0:1], s[0:1], s[4:5]
	s_andn2_b64 vcc, exec, s[0:1]
	s_cbranch_vccnz .LBB0_421
	s_waitcnt vmcnt(0) lgkmcnt(0)
	s_barrier
	v_readlane_b32 s12, v242, 1
	v_readlane_b32 s13, v242, 2
	s_mov_b64 s[14:15], exec
	s_and_b64 s[12:13], s[14:15], s[12:13]
	s_mov_b64 exec, s[12:13]
	s_cbranch_execz .Lxb_done_1
	v_mov_b32_e32 v0, 0x21020
	ds_read2_b32 v[2:3], v0 offset1:1
	s_lshl_b32 s16, s84, 8
	s_add_u32 s16, s76, s16
	s_addc_u32 s17, s77, 0
	v_mov_b32_e32 v1, 0x1000
	v_mov_b32_e32 v4, 1
	global_atomic_add v5, v1, v4, s[16:17] offset:1024 sc0
	buffer_inv sc1
	s_add_u32 s21, s99, 1
	s_waitcnt vmcnt(0) lgkmcnt(0)
	v_readfirstlane_b32 s18, v5
	v_readfirstlane_b32 s19, v2
	v_readfirstlane_b32 s20, v3
	v_mov_b32_e32 v1, 0x3000
	s_mul_i32 s22, s19, s21
	s_mul_i32 s23, s20, s21
	s_add_u32 s18, s18, 1
	s_cmp_lg_u32 s18, s22
	s_cbranch_scc1 .Lxb_spin_1
	buffer_wbl2 sc1
	s_waitcnt vmcnt(0)
	global_atomic_add v1, v4, s[76:77] offset:1024
.Lxb_spin_1:
	global_load_dword v6, v1, s[76:77] offset:1024 sc1
	s_waitcnt vmcnt(0)
	v_readfirstlane_b32 s24, v6
	s_sub_u32 s24, s24, s23
	s_cmp_ge_i32 s24, 0
	s_cbranch_scc1 .Lxb_done_1
	s_sleep 1
	s_branch .Lxb_spin_1
.Lxb_done_1:
	s_mov_b64 exec, s[14:15]
	s_add_u32 s99, s99, 1
	s_barrier

.LBB0_470:
	s_cmp_gt_i32 s79, 3
	s_cselect_b64 s[0:1], -1, 0
	s_and_b64 s[4:5], s[10:11], s[0:1]
	v_readlane_b32 s64, v242, 58
	s_andn2_b64 vcc, exec, s[4:5]
	v_readlane_b32 s65, v242, 59
	s_cbranch_vccnz .LBB0_524
	s_waitcnt vmcnt(0) lgkmcnt(0)
	s_barrier
	v_readlane_b32 s12, v242, 1
	v_readlane_b32 s13, v242, 2
	s_mov_b64 s[14:15], exec
	s_and_b64 s[12:13], s[14:15], s[12:13]
	s_mov_b64 exec, s[12:13]
	s_cbranch_execz .Lxb_done_2
	v_mov_b32_e32 v0, 0x21020
	ds_read2_b32 v[2:3], v0 offset1:1
	s_lshl_b32 s16, s84, 8
	s_add_u32 s16, s76, s16
	s_addc_u32 s17, s77, 0
	v_mov_b32_e32 v1, 0x1000
	v_mov_b32_e32 v4, 1
	global_atomic_add v5, v1, v4, s[16:17] offset:1024 sc0
	buffer_inv sc1
	s_add_u32 s21, s99, 1
	s_waitcnt vmcnt(0) lgkmcnt(0)
	v_readfirstlane_b32 s18, v5
	v_readfirstlane_b32 s19, v2
	v_readfirstlane_b32 s20, v3
	v_mov_b32_e32 v1, 0x3000
	s_mul_i32 s22, s19, s21
	s_mul_i32 s23, s20, s21
	s_add_u32 s18, s18, 1
	s_cmp_lg_u32 s18, s22
	s_cbranch_scc1 .Lxb_spin_2
	buffer_wbl2 sc1
	s_waitcnt vmcnt(0)
	global_atomic_add v1, v4, s[76:77] offset:1024
.Lxb_spin_2:
	global_load_dword v6, v1, s[76:77] offset:1024 sc1
	s_waitcnt vmcnt(0)
	v_readfirstlane_b32 s24, v6
	s_sub_u32 s24, s24, s23
	s_cmp_ge_i32 s24, 0
	s_cbranch_scc1 .Lxb_done_2
	s_sleep 1
	s_branch .Lxb_spin_2
.Lxb_done_2:
	s_mov_b64 exec, s[14:15]
	s_add_u32 s99, s99, 1
	s_barrier

.LBB0_759:
	s_cmp_gt_i32 s79, 4
	s_cselect_b64 s[0:1], -1, 0
	s_and_b64 s[0:1], s[24:25], s[0:1]
	s_andn2_b64 vcc, exec, s[0:1]
	s_cbranch_vccnz .LBB0_813
	s_waitcnt vmcnt(0) lgkmcnt(0)
	s_barrier
	v_readlane_b32 s12, v242, 1
	v_readlane_b32 s13, v242, 2
	s_mov_b64 s[14:15], exec
	s_and_b64 s[12:13], s[14:15], s[12:13]
	s_mov_b64 exec, s[12:13]
	s_cbranch_execz .Lxb_done_3
	v_mov_b32_e32 v0, 0x21020
	ds_read2_b32 v[2:3], v0 offset1:1
	s_lshl_b32 s16, s84, 8
	s_add_u32 s16, s76, s16
	s_addc_u32 s17, s77, 0
	v_mov_b32_e32 v1, 0x1000
	v_mov_b32_e32 v4, 1
	global_atomic_add v5, v1, v4, s[16:17] offset:1024 sc0
	buffer_inv sc1
	s_add_u32 s21, s99, 1
	s_waitcnt vmcnt(0) lgkmcnt(0)
	v_readfirstlane_b32 s18, v5
	v_readfirstlane_b32 s19, v2
	v_readfirstlane_b32 s20, v3
	v_mov_b32_e32 v1, 0x3000
	s_mul_i32 s22, s19, s21
	s_mul_i32 s23, s20, s21
	s_add_u32 s18, s18, 1
	s_cmp_lg_u32 s18, s22
	s_cbranch_scc1 .Lxb_spin_3
	buffer_wbl2 sc1
	s_waitcnt vmcnt(0)
	global_atomic_add v1, v4, s[76:77] offset:1024
.Lxb_spin_3:
	global_load_dword v6, v1, s[76:77] offset:1024 sc1
	s_waitcnt vmcnt(0)
	v_readfirstlane_b32 s24, v6
	s_sub_u32 s24, s24, s23
	s_cmp_ge_i32 s24, 0
	s_cbranch_scc1 .Lxb_done_3
	s_sleep 1
	s_branch .Lxb_spin_3
.Lxb_done_3:
	s_mov_b64 exec, s[14:15]
	s_add_u32 s99, s99, 1
	s_barrier

.LBB0_882:
	s_cmp_gt_i32 s79, 6
	s_cselect_b64 s[0:1], -1, 0
	s_and_b64 s[0:1], s[6:7], s[0:1]
	s_andn2_b64 vcc, exec, s[0:1]
	s_cbranch_vccnz .LBB0_936
	s_waitcnt vmcnt(0) lgkmcnt(0)
	s_barrier
	v_readlane_b32 s12, v242, 1
	v_readlane_b32 s13, v242, 2
	s_mov_b64 s[14:15], exec
	s_and_b64 s[12:13], s[14:15], s[12:13]
	s_mov_b64 exec, s[12:13]
	s_cbranch_execz .Lxb_done_4
	v_mov_b32_e32 v0, 0x21020
	ds_read2_b32 v[2:3], v0 offset1:1
	s_lshl_b32 s16, s84, 8
	s_add_u32 s16, s76, s16
	s_addc_u32 s17, s77, 0
	v_mov_b32_e32 v1, 0x1000
	v_mov_b32_e32 v4, 1
	global_atomic_add v5, v1, v4, s[16:17] offset:1024 sc0
	buffer_inv sc1
	s_add_u32 s21, s99, 1
	s_waitcnt vmcnt(0) lgkmcnt(0)
	v_readfirstlane_b32 s18, v5
	v_readfirstlane_b32 s19, v2
	v_readfirstlane_b32 s20, v3
	v_mov_b32_e32 v1, 0x3000
	s_mul_i32 s22, s19, s21
	s_mul_i32 s23, s20, s21
	s_add_u32 s18, s18, 1
	s_cmp_lg_u32 s18, s22
	s_cbranch_scc1 .Lxb_spin_4
	buffer_wbl2 sc1
	s_waitcnt vmcnt(0)
	global_atomic_add v1, v4, s[76:77] offset:1024
.Lxb_spin_4:
	global_load_dword v6, v1, s[76:77] offset:1024 sc1
	s_waitcnt vmcnt(0)
	v_readfirstlane_b32 s24, v6
	s_sub_u32 s24, s24, s23
	s_cmp_ge_i32 s24, 0
	s_cbranch_scc1 .Lxb_done_4
	s_sleep 1
	s_branch .Lxb_spin_4
.Lxb_done_4:
	s_mov_b64 exec, s[14:15]
	s_add_u32 s99, s99, 1
	s_barrier

.LBB0_952:
	s_cmp_gt_i32 s79, 8
	s_cselect_b64 s[6:7], -1, 0
	s_and_b64 s[0:1], s[4:5], s[6:7]
	s_andn2_b64 vcc, exec, s[0:1]
	s_cbranch_vccnz .LBB0_1006
	s_waitcnt vmcnt(0) lgkmcnt(0)
	s_barrier
	v_readlane_b32 s12, v242, 1
	v_readlane_b32 s13, v242, 2
	s_mov_b64 s[14:15], exec
	s_and_b64 s[12:13], s[14:15], s[12:13]
	s_mov_b64 exec, s[12:13]
	s_cbranch_execz .Lxb_done_5
	v_mov_b32_e32 v0, 0x21020
	ds_read2_b32 v[2:3], v0 offset1:1
	s_lshl_b32 s16, s84, 8
	s_add_u32 s16, s76, s16
	s_addc_u32 s17, s77, 0
	v_mov_b32_e32 v1, 0x1000
	v_mov_b32_e32 v4, 1
	global_atomic_add v5, v1, v4, s[16:17] offset:1024 sc0
	buffer_inv sc1
	s_add_u32 s21, s99, 1
	s_waitcnt vmcnt(0) lgkmcnt(0)
	v_readfirstlane_b32 s18, v5
	v_readfirstlane_b32 s19, v2
	v_readfirstlane_b32 s20, v3
	v_mov_b32_e32 v1, 0x3000
	s_mul_i32 s22, s19, s21
	s_mul_i32 s23, s20, s21
	s_add_u32 s18, s18, 1
	s_cmp_lg_u32 s18, s22
	s_cbranch_scc1 .Lxb_spin_5
	buffer_wbl2 sc1
	s_waitcnt vmcnt(0)
	global_atomic_add v1, v4, s[76:77] offset:1024
.Lxb_spin_5:
	global_load_dword v6, v1, s[76:77] offset:1024 sc1
	s_waitcnt vmcnt(0)
	v_readfirstlane_b32 s24, v6
	s_sub_u32 s24, s24, s23
	s_cmp_ge_i32 s24, 0
	s_cbranch_scc1 .Lxb_done_5
	s_sleep 1
	s_branch .Lxb_spin_5
.Lxb_done_5:
	s_mov_b64 exec, s[14:15]
	s_add_u32 s99, s99, 1
	s_barrier

.LBB0_1051:
	s_cmp_gt_i32 s79, 9
	s_cselect_b64 s[4:5], -1, 0
	s_and_b64 s[0:1], s[0:1], s[4:5]
	s_andn2_b64 vcc, exec, s[0:1]
	s_cbranch_vccnz .LBB0_1105
	s_waitcnt vmcnt(0) lgkmcnt(0)
	s_barrier
	v_readlane_b32 s12, v242, 1
	v_readlane_b32 s13, v242, 2
	s_mov_b64 s[14:15], exec
	s_and_b64 s[12:13], s[14:15], s[12:13]
	s_mov_b64 exec, s[12:13]
	s_cbranch_execz .Lxb_done_6
	v_mov_b32_e32 v0, 0x21020
	ds_read2_b32 v[2:3], v0 offset1:1
	s_lshl_b32 s16, s84, 8
	s_add_u32 s16, s76, s16
	s_addc_u32 s17, s77, 0
	v_mov_b32_e32 v1, 0x1000
	v_mov_b32_e32 v4, 1
	global_atomic_add v5, v1, v4, s[16:17] offset:1024 sc0
	buffer_inv sc1
	s_add_u32 s21, s99, 1
	s_waitcnt vmcnt(0) lgkmcnt(0)
	v_readfirstlane_b32 s18, v5
	v_readfirstlane_b32 s19, v2
	v_readfirstlane_b32 s20, v3
	v_mov_b32_e32 v1, 0x3000
	s_mul_i32 s22, s19, s21
	s_mul_i32 s23, s20, s21
	s_add_u32 s18, s18, 1
	s_cmp_lg_u32 s18, s22
	s_cbranch_scc1 .Lxb_spin_6
	buffer_wbl2 sc1
	s_waitcnt vmcnt(0)
	global_atomic_add v1, v4, s[76:77] offset:1024
.Lxb_spin_6:
	global_load_dword v6, v1, s[76:77] offset:1024 sc1
	s_waitcnt vmcnt(0)
	v_readfirstlane_b32 s24, v6
	s_sub_u32 s24, s24, s23
	s_cmp_ge_i32 s24, 0
	s_cbranch_scc1 .Lxb_done_6
	s_sleep 1
	s_branch .Lxb_spin_6
.Lxb_done_6:
	s_mov_b64 exec, s[14:15]
	s_add_u32 s99, s99, 1
	s_barrier

.LBB0_1246:
	s_cmp_gt_i32 s79, 10
	s_cselect_b64 s[4:5], -1, 0
	s_and_b64 s[0:1], s[0:1], s[4:5]
	s_andn2_b64 vcc, exec, s[0:1]
	s_cbranch_vccnz .LBB0_1300
	s_waitcnt vmcnt(0) lgkmcnt(0)
	s_barrier
	v_readlane_b32 s12, v242, 1
	v_readlane_b32 s13, v242, 2
	s_mov_b64 s[14:15], exec
	s_and_b64 s[12:13], s[14:15], s[12:13]
	s_mov_b64 exec, s[12:13]
	s_cbranch_execz .Lxb_done_7
	v_mov_b32_e32 v0, 0x21020
	ds_read2_b32 v[2:3], v0 offset1:1
	s_lshl_b32 s16, s84, 8
	s_add_u32 s16, s76, s16
	s_addc_u32 s17, s77, 0
	v_mov_b32_e32 v1, 0x1000
	v_mov_b32_e32 v4, 1
	global_atomic_add v5, v1, v4, s[16:17] offset:1024 sc0
	buffer_inv sc1
	s_add_u32 s21, s99, 1
	s_waitcnt vmcnt(0) lgkmcnt(0)
	v_readfirstlane_b32 s18, v5
	v_readfirstlane_b32 s19, v2
	v_readfirstlane_b32 s20, v3
	v_mov_b32_e32 v1, 0x3000
	s_mul_i32 s22, s19, s21
	s_mul_i32 s23, s20, s21
	s_add_u32 s18, s18, 1
	s_cmp_lg_u32 s18, s22
	s_cbranch_scc1 .Lxb_spin_7
	buffer_wbl2 sc1
	s_waitcnt vmcnt(0)
	global_atomic_add v1, v4, s[76:77] offset:1024
.Lxb_spin_7:
	global_load_dword v6, v1, s[76:77] offset:1024 sc1
	s_waitcnt vmcnt(0)
	v_readfirstlane_b32 s24, v6
	s_sub_u32 s24, s24, s23
	s_cmp_ge_i32 s24, 0
	s_cbranch_scc1 .Lxb_done_7
	s_sleep 1
	s_branch .Lxb_spin_7
.Lxb_done_7:
	s_mov_b64 exec, s[14:15]
	s_add_u32 s99, s99, 1
	s_barrier

.LBB0_1349:
	s_cmp_gt_i32 s79, 11
	s_cselect_b64 s[4:5], -1, 0
	s_and_b64 s[0:1], s[10:11], s[4:5]
	s_andn2_b64 vcc, exec, s[0:1]
	s_cbranch_vccnz .LBB0_1403
	s_waitcnt vmcnt(0) lgkmcnt(0)
	s_barrier
	v_readlane_b32 s12, v242, 1
	v_readlane_b32 s13, v242, 2
	s_mov_b64 s[14:15], exec
	s_and_b64 s[12:13], s[14:15], s[12:13]
	s_mov_b64 exec, s[12:13]
	s_cbranch_execz .Lxb_done_8
	v_mov_b32_e32 v0, 0x21020
	ds_read2_b32 v[2:3], v0 offset1:1
	s_lshl_b32 s16, s84, 8
	s_add_u32 s16, s76, s16
	s_addc_u32 s17, s77, 0
	v_mov_b32_e32 v1, 0x1000
	v_mov_b32_e32 v4, 1
	global_atomic_add v5, v1, v4, s[16:17] offset:1024 sc0
	buffer_inv sc1
	s_add_u32 s21, s99, 1
	s_waitcnt vmcnt(0) lgkmcnt(0)
	v_readfirstlane_b32 s18, v5
	v_readfirstlane_b32 s19, v2
	v_readfirstlane_b32 s20, v3
	v_mov_b32_e32 v1, 0x3000
	s_mul_i32 s22, s19, s21
	s_mul_i32 s23, s20, s21
	s_add_u32 s18, s18, 1
	s_cmp_lg_u32 s18, s22
	s_cbranch_scc1 .Lxb_spin_8
	buffer_wbl2 sc1
	s_waitcnt vmcnt(0)
	global_atomic_add v1, v4, s[76:77] offset:1024
.Lxb_spin_8:
	global_load_dword v6, v1, s[76:77] offset:1024 sc1
	s_waitcnt vmcnt(0)
	v_readfirstlane_b32 s24, v6
	s_sub_u32 s24, s24, s23
	s_cmp_ge_i32 s24, 0
	s_cbranch_scc1 .Lxb_done_8
	s_sleep 1
	s_branch .Lxb_spin_8
.Lxb_done_8:
	s_mov_b64 exec, s[14:15]
	s_add_u32 s99, s99, 1
	s_barrier

.LBB0_1552:
	s_cmp_gt_i32 s79, 12
	s_cselect_b64 s[4:5], -1, 0
	s_and_b64 s[0:1], s[0:1], s[4:5]
	s_andn2_b64 vcc, exec, s[0:1]
	s_cbranch_vccnz .LBB0_1606
	s_waitcnt vmcnt(0) lgkmcnt(0)
	s_barrier
	v_readlane_b32 s12, v242, 1
	v_readlane_b32 s13, v242, 2
	s_mov_b64 s[14:15], exec
	s_and_b64 s[12:13], s[14:15], s[12:13]
	s_mov_b64 exec, s[12:13]
	s_cbranch_execz .Lxb_done_9
	v_mov_b32_e32 v0, 0x21020
	ds_read2_b32 v[2:3], v0 offset1:1
	s_lshl_b32 s16, s84, 8
	s_add_u32 s16, s76, s16
	s_addc_u32 s17, s77, 0
	v_mov_b32_e32 v1, 0x1000
	v_mov_b32_e32 v4, 1
	global_atomic_add v5, v1, v4, s[16:17] offset:1024 sc0
	buffer_inv sc1
	s_add_u32 s21, s99, 1
	s_waitcnt vmcnt(0) lgkmcnt(0)
	v_readfirstlane_b32 s18, v5
	v_readfirstlane_b32 s19, v2
	v_readfirstlane_b32 s20, v3
	v_mov_b32_e32 v1, 0x3000
	s_mul_i32 s22, s19, s21
	s_mul_i32 s23, s20, s21
	s_add_u32 s18, s18, 1
	s_cmp_lg_u32 s18, s22
	s_cbranch_scc1 .Lxb_spin_9
	buffer_wbl2 sc1
	s_waitcnt vmcnt(0)
	global_atomic_add v1, v4, s[76:77] offset:1024
.Lxb_spin_9:
	global_load_dword v6, v1, s[76:77] offset:1024 sc1
	s_waitcnt vmcnt(0)
	v_readfirstlane_b32 s24, v6
	s_sub_u32 s24, s24, s23
	s_cmp_ge_i32 s24, 0
	s_cbranch_scc1 .Lxb_done_9
	s_sleep 1
	s_branch .Lxb_spin_9
.Lxb_done_9:
	s_mov_b64 exec, s[14:15]
	s_add_u32 s99, s99, 1
	s_barrier

.LBB0_1655:
	s_cmp_gt_i32 s79, 13
	s_cselect_b64 s[4:5], -1, 0
	s_and_b64 s[0:1], s[10:11], s[4:5]
	s_andn2_b64 vcc, exec, s[0:1]
	s_cbranch_vccnz .LBB0_1709
	s_waitcnt vmcnt(0) lgkmcnt(0)
	s_barrier
	v_readlane_b32 s12, v242, 1
	v_readlane_b32 s13, v242, 2
	s_mov_b64 s[14:15], exec
	s_and_b64 s[12:13], s[14:15], s[12:13]
	s_mov_b64 exec, s[12:13]
	s_cbranch_execz .Lxb_done_10
	v_mov_b32_e32 v0, 0x21020
	ds_read2_b32 v[2:3], v0 offset1:1
	s_lshl_b32 s16, s84, 8
	s_add_u32 s16, s76, s16
	s_addc_u32 s17, s77, 0
	v_mov_b32_e32 v1, 0x1000
	v_mov_b32_e32 v4, 1
	global_atomic_add v5, v1, v4, s[16:17] offset:1024 sc0
	buffer_inv sc1
	s_add_u32 s21, s99, 1
	s_waitcnt vmcnt(0) lgkmcnt(0)
	v_readfirstlane_b32 s18, v5
	v_readfirstlane_b32 s19, v2
	v_readfirstlane_b32 s20, v3
	v_mov_b32_e32 v1, 0x3000
	s_mul_i32 s22, s19, s21
	s_mul_i32 s23, s20, s21
	s_add_u32 s18, s18, 1
	s_cmp_lg_u32 s18, s22
	s_cbranch_scc1 .Lxb_spin_10
	buffer_wbl2 sc1
	s_waitcnt vmcnt(0)
	global_atomic_add v1, v4, s[76:77] offset:1024
.Lxb_spin_10:
	global_load_dword v6, v1, s[76:77] offset:1024 sc1
	s_waitcnt vmcnt(0)
	v_readfirstlane_b32 s24, v6
	s_sub_u32 s24, s24, s23
	s_cmp_ge_i32 s24, 0
	s_cbranch_scc1 .Lxb_done_10
	s_sleep 1
	s_branch .Lxb_spin_10
.Lxb_done_10:
	s_mov_b64 exec, s[14:15]
	s_add_u32 s99, s99, 1
	s_barrier

.LBB0_1734:
	s_cmp_gt_i32 s79, 14
	s_cselect_b64 s[4:5], -1, 0
	s_and_b64 s[0:1], s[0:1], s[4:5]
	s_andn2_b64 vcc, exec, s[0:1]
	s_cbranch_vccnz .LBB0_1788
	s_waitcnt vmcnt(0) lgkmcnt(0)
	s_barrier
	v_readlane_b32 s12, v242, 1
	v_readlane_b32 s13, v242, 2
	s_mov_b64 s[14:15], exec
	s_and_b64 s[12:13], s[14:15], s[12:13]
	s_mov_b64 exec, s[12:13]
	s_cbranch_execz .Lxb_done_11
	v_mov_b32_e32 v0, 0x21020
	ds_read2_b32 v[2:3], v0 offset1:1
	s_lshl_b32 s16, s84, 8
	s_add_u32 s16, s76, s16
	s_addc_u32 s17, s77, 0
	v_mov_b32_e32 v1, 0x1000
	v_mov_b32_e32 v4, 1
	global_atomic_add v5, v1, v4, s[16:17] offset:1024 sc0
	buffer_inv sc1
	s_add_u32 s21, s99, 1
	s_waitcnt vmcnt(0) lgkmcnt(0)
	v_readfirstlane_b32 s18, v5
	v_readfirstlane_b32 s19, v2
	v_readfirstlane_b32 s20, v3
	v_mov_b32_e32 v1, 0x3000
	s_mul_i32 s22, s19, s21
	s_mul_i32 s23, s20, s21
	s_add_u32 s18, s18, 1
	s_cmp_lg_u32 s18, s22
	s_cbranch_scc1 .Lxb_spin_11
	buffer_wbl2 sc1
	s_waitcnt vmcnt(0)
	global_atomic_add v1, v4, s[76:77] offset:1024
.Lxb_spin_11:
	global_load_dword v6, v1, s[76:77] offset:1024 sc1
	s_waitcnt vmcnt(0)
	v_readfirstlane_b32 s24, v6
	s_sub_u32 s24, s24, s23
	s_cmp_ge_i32 s24, 0
	s_cbranch_scc1 .Lxb_done_11
	s_sleep 1
	s_branch .Lxb_spin_11
.Lxb_done_11:
	s_mov_b64 exec, s[14:15]
	s_add_u32 s99, s99, 1
	s_barrier

.LBB0_1812:
	s_cmp_gt_i32 s79, 15
	s_cselect_b64 s[4:5], -1, 0
	s_and_b64 s[0:1], s[0:1], s[4:5]
	s_andn2_b64 vcc, exec, s[0:1]
	s_cbranch_vccnz .LBB0_1866
	s_waitcnt vmcnt(0) lgkmcnt(0)
	s_barrier
	v_readlane_b32 s12, v242, 1
	v_readlane_b32 s13, v242, 2
	s_mov_b64 s[14:15], exec
	s_and_b64 s[12:13], s[14:15], s[12:13]
	s_mov_b64 exec, s[12:13]
	s_cbranch_execz .Lxb_done_12
	v_mov_b32_e32 v0, 0x21020
	ds_read2_b32 v[2:3], v0 offset1:1
	s_lshl_b32 s16, s84, 8
	s_add_u32 s16, s76, s16
	s_addc_u32 s17, s77, 0
	v_mov_b32_e32 v1, 0x1000
	v_mov_b32_e32 v4, 1
	global_atomic_add v5, v1, v4, s[16:17] offset:1024 sc0
	buffer_inv sc1
	s_add_u32 s21, s99, 1
	s_waitcnt vmcnt(0) lgkmcnt(0)
	v_readfirstlane_b32 s18, v5
	v_readfirstlane_b32 s19, v2
	v_readfirstlane_b32 s20, v3
	v_mov_b32_e32 v1, 0x3000
	s_mul_i32 s22, s19, s21
	s_mul_i32 s23, s20, s21
	s_add_u32 s18, s18, 1
	s_cmp_lg_u32 s18, s22
	s_cbranch_scc1 .Lxb_spin_12
	buffer_wbl2 sc1
	s_waitcnt vmcnt(0)
	global_atomic_add v1, v4, s[76:77] offset:1024
.Lxb_spin_12:
	global_load_dword v6, v1, s[76:77] offset:1024 sc1
	s_waitcnt vmcnt(0)
	v_readfirstlane_b32 s24, v6
	s_sub_u32 s24, s24, s23
	s_cmp_ge_i32 s24, 0
	s_cbranch_scc1 .Lxb_done_12
	s_sleep 1
	s_branch .Lxb_spin_12
.Lxb_done_12:
	s_mov_b64 exec, s[14:15]
	s_add_u32 s99, s99, 1
	s_barrier

.LBB0_1911:
	s_cmp_gt_i32 s79, 16
	s_cselect_b64 s[4:5], -1, 0
	s_and_b64 s[0:1], s[0:1], s[4:5]
	s_andn2_b64 vcc, exec, s[0:1]
	s_cbranch_vccnz .LBB0_1965
	s_waitcnt vmcnt(0) lgkmcnt(0)
	s_barrier
	v_readlane_b32 s12, v242, 1
	v_readlane_b32 s13, v242, 2
	s_mov_b64 s[14:15], exec
	s_and_b64 s[12:13], s[14:15], s[12:13]
	s_mov_b64 exec, s[12:13]
	s_cbranch_execz .Lxb_done_13
	v_mov_b32_e32 v0, 0x21020
	ds_read2_b32 v[2:3], v0 offset1:1
	s_lshl_b32 s16, s84, 8
	s_add_u32 s16, s76, s16
	s_addc_u32 s17, s77, 0
	v_mov_b32_e32 v1, 0x1000
	v_mov_b32_e32 v4, 1
	global_atomic_add v5, v1, v4, s[16:17] offset:1024 sc0
	buffer_inv sc1
	s_add_u32 s21, s99, 1
	s_waitcnt vmcnt(0) lgkmcnt(0)
	v_readfirstlane_b32 s18, v5
	v_readfirstlane_b32 s19, v2
	v_readfirstlane_b32 s20, v3
	v_mov_b32_e32 v1, 0x3000
	s_mul_i32 s22, s19, s21
	s_mul_i32 s23, s20, s21
	s_add_u32 s18, s18, 1
	s_cmp_lg_u32 s18, s22
	s_cbranch_scc1 .Lxb_spin_13
	buffer_wbl2 sc1
	s_waitcnt vmcnt(0)
	global_atomic_add v1, v4, s[76:77] offset:1024
.Lxb_spin_13:
	global_load_dword v6, v1, s[76:77] offset:1024 sc1
	s_waitcnt vmcnt(0)
	v_readfirstlane_b32 s24, v6
	s_sub_u32 s24, s24, s23
	s_cmp_ge_i32 s24, 0
	s_cbranch_scc1 .Lxb_done_13
	s_sleep 1
	s_branch .Lxb_spin_13
.Lxb_done_13:
	s_mov_b64 exec, s[14:15]
	s_add_u32 s99, s99, 1
	s_barrier

.LBB0_1982:
	s_cmp_gt_i32 s79, 17
	s_cselect_b64 s[4:5], -1, 0
	s_and_b64 s[0:1], s[0:1], s[4:5]
	s_andn2_b64 vcc, exec, s[0:1]
	s_cbranch_vccnz .LBB0_2036
	s_waitcnt vmcnt(0) lgkmcnt(0)
	s_barrier
	v_readlane_b32 s12, v242, 1
	v_readlane_b32 s13, v242, 2
	s_mov_b64 s[14:15], exec
	s_and_b64 s[12:13], s[14:15], s[12:13]
	s_mov_b64 exec, s[12:13]
	s_cbranch_execz .Lxb_done_14
	v_mov_b32_e32 v0, 0x21020
	ds_read2_b32 v[2:3], v0 offset1:1
	s_lshl_b32 s16, s84, 8
	s_add_u32 s16, s76, s16
	s_addc_u32 s17, s77, 0
	v_mov_b32_e32 v1, 0x1000
	v_mov_b32_e32 v4, 1
	global_atomic_add v5, v1, v4, s[16:17] offset:1024 sc0
	buffer_inv sc1
	s_add_u32 s21, s99, 1
	s_waitcnt vmcnt(0) lgkmcnt(0)
	v_readfirstlane_b32 s18, v5
	v_readfirstlane_b32 s19, v2
	v_readfirstlane_b32 s20, v3
	v_mov_b32_e32 v1, 0x3000
	s_mul_i32 s22, s19, s21
	s_mul_i32 s23, s20, s21
	s_add_u32 s18, s18, 1
	s_cmp_lg_u32 s18, s22
	s_cbranch_scc1 .Lxb_spin_14
	buffer_wbl2 sc1
	s_waitcnt vmcnt(0)
	global_atomic_add v1, v4, s[76:77] offset:1024
.Lxb_spin_14:
	global_load_dword v6, v1, s[76:77] offset:1024 sc1
	s_waitcnt vmcnt(0)
	v_readfirstlane_b32 s24, v6
	s_sub_u32 s24, s24, s23
	s_cmp_ge_i32 s24, 0
	s_cbranch_scc1 .Lxb_done_14
	s_sleep 1
	s_branch .Lxb_spin_14
.Lxb_done_14:
	s_mov_b64 exec, s[14:15]
	s_add_u32 s99, s99, 1
	s_barrier
